# fox kv loop: cross-half row-max via v_permlane32_swap instead of ds_bpermute round trip (bit-identical)
# baseline (speedup 1.0000x reference)
.LBB0_336:
	s_nop 8
	v_mov_b32_e32 v32, v152
	s_nop 1
	v_permlane32_swap_b32_e32 v32, v152
	v_max3_f32 v33, v151, v152, v32
	v_sub_f32_e32 v34, v114, v33
	v_exp_f32_e32 v52, v34
	v_sub_f32_e32 v34, v119, v33
	v_sub_f32_e32 v36, v115, v33
	v_exp_f32_e32 v115, v34
	v_sub_f32_e32 v34, v116, v33
	v_exp_f32_e32 v54, v34
	v_sub_f32_e32 v34, v120, v33
	v_exp_f32_e32 v116, v34
	v_sub_f32_e32 v34, v117, v33
	v_exp_f32_e32 v117, v34
	v_sub_f32_e32 v34, v121, v33
	v_exp_f32_e32 v121, v34
	v_sub_f32_e32 v34, v122, v33
	v_sub_f32_e32 v48, v138, v33
	v_add_u32_e32 v122, 0x2000, v149
	v_exp_f32_e32 v61, v48
	ds_read2_b64 v[48:51], v122 offset0:128 offset1:130
	v_sub_f32_e32 v32, v151, v33
	v_sub_f32_e32 v35, v118, v33
	v_exp_f32_e32 v32, v32
	v_exp_f32_e32 v114, v35
	v_exp_f32_e32 v53, v36
	v_exp_f32_e32 v35, v34
	v_sub_f32_e32 v34, v124, v33
	v_sub_f32_e32 v38, v126, v33
	v_exp_f32_e32 v37, v34
	v_sub_f32_e32 v34, v123, v33
	v_exp_f32_e32 v39, v38
	v_sub_f32_e32 v38, v128, v33
	v_add_u32_e32 v123, 0x3000, v149
	v_exp_f32_e32 v41, v38
	v_sub_f32_e32 v38, v127, v33
	v_pk_mul_f32 v[30:31], v[30:31], v[32:33] op_sel_hi:[1,0]
	v_pk_mul_f32 v[28:29], v[28:29], v[32:33] op_sel_hi:[1,0]
	v_pk_mul_f32 v[26:27], v[26:27], v[32:33] op_sel_hi:[1,0]
	v_pk_mul_f32 v[24:25], v[24:25], v[32:33] op_sel_hi:[1,0]
	v_pk_mul_f32 v[22:23], v[22:23], v[32:33] op_sel_hi:[1,0]
	v_pk_mul_f32 v[20:21], v[20:21], v[32:33] op_sel_hi:[1,0]
	v_pk_mul_f32 v[18:19], v[18:19], v[32:33] op_sel_hi:[1,0]
	v_pk_mul_f32 v[16:17], v[16:17], v[32:33] op_sel_hi:[1,0]
	ds_read2_b64 v[56:59], v123 offset0:192 offset1:194
	v_add_f32_e32 v118, v52, v114
	v_add_f32_e32 v119, v53, v115
	v_add_f32_e32 v120, v54, v116
	v_exp_f32_e32 v34, v34
	v_exp_f32_e32 v38, v38
	v_cvt_pk_bf16_f32 v52, v52, v53
	v_cvt_pk_bf16_f32 v53, v54, v117
	v_cvt_pk_bf16_f32 v54, v35, v34
	v_cvt_pk_bf16_f32 v55, v39, v38
	v_sub_f32_e32 v42, v130, v33
	s_waitcnt lgkmcnt(1)
	v_mfma_f32_32x32x16_bf16 v[16:31], v[48:51], v[52:55], v[16:31]
	ds_read2_b64 v[48:51], v122 offset0:132 offset1:134
	v_sub_f32_e32 v44, v132, v33
	v_sub_f32_e32 v46, v140, v33
	v_mul_f32_e64 v14, v14, v32
	v_mul_f32_e64 v15, v15, v32
	v_pk_mul_f32 v[12:13], v[12:13], v[32:33] op_sel_hi:[1,0]
	v_pk_mul_f32 v[10:11], v[10:11], v[32:33] op_sel_hi:[1,0]
	v_pk_mul_f32 v[8:9], v[8:9], v[32:33] op_sel_hi:[1,0]
	v_pk_mul_f32 v[6:7], v[6:7], v[32:33] op_sel_hi:[1,0]
	v_pk_mul_f32 v[4:5], v[4:5], v[32:33] op_sel_hi:[1,0]
	v_pk_mul_f32 v[2:3], v[2:3], v[32:33] op_sel_hi:[1,0]
	v_pk_mul_f32 v[0:1], v[0:1], v[32:33] op_sel_hi:[1,0]
	v_exp_f32_e32 v43, v42
	v_sub_f32_e32 v42, v131, v33
	v_exp_f32_e32 v45, v44
	v_sub_f32_e32 v44, v133, v33
	v_exp_f32_e32 v47, v46
	v_sub_f32_e32 v46, v141, v33
	s_waitcnt lgkmcnt(1)
	v_mfma_f32_32x32x16_bf16 v[0:15], v[56:59], v[52:55], v[0:15]
	v_sub_f32_e32 v52, v139, v33
	v_exp_f32_e32 v42, v42
	v_exp_f32_e32 v44, v44
	v_exp_f32_e32 v46, v46
	v_exp_f32_e32 v60, v52
	v_cvt_pk_bf16_f32 v52, v43, v42
	v_cvt_pk_bf16_f32 v53, v45, v44
	v_cvt_pk_bf16_f32 v54, v47, v46
	v_cvt_pk_bf16_f32 v55, v61, v60
	ds_read2_b64 v[56:59], v123 offset0:196 offset1:198
	s_waitcnt lgkmcnt(1)
	v_mfma_f32_32x32x16_bf16 v[16:31], v[48:51], v[52:55], v[16:31]
	v_sub_f32_e32 v48, v96, v33
	v_exp_f32_e32 v63, v48
	v_sub_f32_e32 v48, v97, v33
	v_exp_f32_e32 v62, v48
	v_sub_f32_e32 v48, v98, v33
	v_exp_f32_e32 v97, v48
	ds_read2_b64 v[48:51], v122 offset0:136 offset1:138
	v_sub_f32_e32 v36, v125, v33
	v_sub_f32_e32 v40, v129, v33
	s_waitcnt lgkmcnt(1)
	v_mfma_f32_32x32x16_bf16 v[0:15], v[56:59], v[52:55], v[0:15]
	v_sub_f32_e32 v52, v99, v33
	v_exp_f32_e32 v36, v36
	v_exp_f32_e32 v40, v40
	v_exp_f32_e32 v96, v52
	v_cvt_pk_bf16_f32 v52, v114, v115
	v_cvt_pk_bf16_f32 v53, v116, v121
	v_cvt_pk_bf16_f32 v54, v37, v36
	v_cvt_pk_bf16_f32 v55, v41, v40
	ds_read2_b64 v[56:59], v123 offset0:200 offset1:202
	s_waitcnt lgkmcnt(1)
	v_mfma_f32_32x32x16_bf16 v[16:31], v[48:51], v[52:55], v[16:31]
	v_sub_f32_e32 v48, v134, v33
	v_exp_f32_e32 v99, v48
	v_sub_f32_e32 v48, v135, v33
	v_exp_f32_e32 v98, v48
	v_sub_f32_e32 v48, v136, v33
	v_exp_f32_e32 v115, v48
	ds_read2_b64 v[48:51], v122 offset0:140 offset1:142
	v_pk_add_f32 v[34:35], v[34:35], v[36:37]
	v_pk_add_f32 v[36:37], v[38:39], v[40:41]
	v_pk_add_f32 v[38:39], v[42:43], v[62:63]
	v_pk_add_f32 v[42:43], v[46:47], v[98:99]
	v_add_f32_e32 v46, 0, v118
	s_waitcnt lgkmcnt(1)
	v_mfma_f32_32x32x16_bf16 v[0:15], v[56:59], v[52:55], v[0:15]
	v_sub_f32_e32 v52, v137, v33
	ds_read2_b64 v[56:59], v123 offset0:204 offset1:206
	v_add_f32_e32 v46, v119, v46
	v_exp_f32_e32 v114, v52
	v_cvt_pk_bf16_f32 v52, v63, v62
	v_cvt_pk_bf16_f32 v53, v97, v96
	v_cvt_pk_bf16_f32 v54, v99, v98
	v_cvt_pk_bf16_f32 v55, v115, v114
	v_add_f32_e32 v46, v120, v46
	s_waitcnt lgkmcnt(1)
	v_mfma_f32_32x32x16_bf16 v[16:31], v[48:51], v[52:55], v[16:31]
	v_add_f32_e32 v48, v117, v121
	v_add_f32_e32 v46, v48, v46
	v_add_f32_e32 v35, v35, v46
	v_add_f32_e32 v34, v34, v35
	v_add_f32_e32 v34, v37, v34
	v_add_f32_e32 v34, v36, v34
	v_add_f32_e32 v34, v39, v34
	v_pk_add_f32 v[40:41], v[44:45], v[96:97]
	v_add_f32_e32 v34, v38, v34
	s_waitcnt lgkmcnt(0)
	v_mfma_f32_32x32x16_bf16 v[0:15], v[56:59], v[52:55], v[0:15]
	v_add_f32_e32 v34, v41, v34
	v_add_f32_e32 v34, v40, v34
	v_add_f32_e32 v34, v43, v34
	v_add_f32_e64 v44, v60, v114
	v_add_f32_e64 v45, v61, v115
	v_add_f32_e32 v34, v42, v34
	v_add_f32_e32 v34, v45, v34
	v_add_f32_e32 v34, v44, v34
	v_fmac_f32_e32 v34, v109, v32
	v_mov_b32_e32 v151, v33
	v_mov_b32_e32 v109, v34
